# mix0 dynamic queue: 3:1 attention/gmlp interleave for the first 2048 entries, then 512 attention, last 512 gmlp tiles as tail
# speedup vs baseline: 1.0023x; 1.0023x over previous
.Lmy_m0_map:
	s_cmpk_lt_i32 s93, 0xc00
	s_cbranch_scc0 .LBB0_261
	s_mov_b32 s88, s93
	s_cmpk_ge_i32 s93, 0xa00
	s_cbranch_scc1 .Lmy_m0_mapped
	s_sub_i32 s88, s93, 0x200
	s_cmpk_ge_i32 s93, 0x800
	s_cbranch_scc1 .Lmy_m0_mapped
	s_lshr_b32 s98, s93, 2
	s_and_b32 s100, s93, 3
	s_mul_i32 s88, s98, 3
	s_add_i32 s88, s88, s100
	s_add_i32 s98, s98, 0x800
	s_cmp_eq_u32 s100, 3
	s_cselect_b32 s88, s98, s88
